# static s_setprio 1 for waves 4-7 inside the three scan loops, on top of MFMA order
# speedup vs baseline: 1.0060x; 1.0060x over previous
; #define LAS __attribute__((address_space(3)))
; DI void hgrn2_scan_unit(Frame& F, const Mix0Args& a, int u) {
;     const int tid = F.tid, w = F.wave, lane = F.lane, fr = lane & 15, fq = lane >> 4;
;     const int b = u >> 7, h = (u >> 2) & 31, vs = u & 3;
;     constexpr int VIMG = 32 * S64;
;     LAS uchar* VT0 = F.lds; LAS uchar* STB0 = VT0 + 2 * VIMG;
;     const int ltile = w & 3, jtile = w >> 2, l0_ = 16 * ltile, v0_ = 16 * jtile;
;     const f32x4 anw = *(const f32x4*)(a.a_norm_w + h * 128 + vs * 32 + v0_ + 4 * fq);
;     const int vp = tid & 15, lr = tid >> 4;
;     for (int i = tid; i < 32 * S128 / 16; i += 512) ((LAS u32x4*)STB0)[i] = (u32x4){0u, 0u, 0u, 0u};
;     f32x4 st[2] = {(f32x4){0.f, 0.f, 0.f, 0.f}, (f32x4){0.f, 0.f, 0.f, 0.f}};
;     const size_t rowbase = (size_t)b * SEQ; const size_t Tb = ((size_t)(b * 32 + h)) * 128;
;     const unsigned voq = (unsigned)((ltile * 256 + lane) * 16), vop = (unsigned)((ltile * 128 + lane) * 16), vok = (unsigned)((w * 128 + lane) * 16), vog = (unsigned)((16 * w + 4 * fq) * 4);
;     unsigned vov[2];
; #pragma unroll
;     for (int i = 0; i < 2; ++i) vov[i] = (unsigned)((2 * lr + i) * N1 + C_I + h * 128 + vs * 32 + 2 * vp) * 2u;
;     const unsigned voga = (unsigned)((l0_ + fr) * N1 + C_GA + h * 128 + vs * 32 + v0_ + 4 * fq) * 2u;
;     const unsigned voo = (unsigned)((l0_ + fr) * a.out_ld + a.oa_col + h * 128 + vs * 32 + v0_ + 4 * fq) * 2u, vos = (unsigned)(l0_ + fr) * 4u;
;     const char* const pQ = (const char*)a.Qg; const char* const pPm = (const char*)a.Pg; const char* const pK = (const char*)a.KSTg; const char* const pG = (const char*)a.GLg;
;     const char* const pE = (const char*)a.EREFg; const char* const pP = (const char*)a.proj; char* const pO = (char*)a.outp; char* const pS = (char*)a.ssq_a;
.LBB0_203:
	v_readlane_b32 s4, v253, 22
	v_readlane_b32 s5, v253, 23
	s_cmp_lt_i32 s4, 4
	s_cselect_b64 s[0:1], -1, 0
	s_cmp_gt_i32 s5, 3
	s_cselect_b64 s[4:5], -1, 0
	s_and_b64 s[0:1], s[0:1], s[4:5]
	s_andn2_b64 vcc, exec, s[0:1]
	v_readlane_b32 s6, v253, 24
	v_readlane_b32 s7, v253, 25
	s_cbranch_vccnz .LBB0_412
	v_readlane_b32 s0, v253, 2
	s_cmpk_gt_i32 s0, 0xff
	s_cbranch_scc1 .LBB0_362
	v_readlane_b32 s0, v253, 41
	v_readlane_b32 s1, v253, 42
	s_and_b64 s[0:1], s[0:1], exec
	v_readlane_b32 s2, v253, 53
	v_readlane_b32 s0, v253, 44
	v_readlane_b32 s3, v253, 54
	s_cselect_b32 s3, s3, s0
	v_readlane_b32 s0, v253, 43
	s_cselect_b32 s2, s2, s0
	s_movk_i32 s0, 0x2000
	v_readlane_b32 s9, v253, 26
	s_cselect_b32 s4, s0, 0x1000
	s_cmp_gt_u32 s9, 3
	s_cbranch_scc0 .Lhg_noprio
	s_setprio 1
.Lhg_noprio:
	v_readlane_b32 s12, v253, 34
	s_lshl_b32 s0, s9, 2
	s_bfe_u32 s26, s12, 0x20006
	s_and_b32 s25, s0, 0xffffff0
	s_and_b32 s5, s12, 0xffffffc0
	v_and_b32_e32 v102, 48, v0
	v_and_b32_e32 v105, 15, v0
	s_lshl_b32 s24, s26, 4
	v_lshlrev_b32_e32 v2, 4, v166
	v_or_b32_e32 v114, s5, v102
	s_add_i32 s5, s25, 0x3000
	v_lshl_or_b32 v108, s9, 11, v2
	s_movk_i32 s8, 0x6000
	v_lshl_or_b32 v110, s26, 12, v2
	v_lshl_or_b32 v112, s26, 11, v2
	v_or_b32_e32 v170, s24, v105
	v_mov_b32_e32 v2, s5
	s_add_i32 s4, s25, s4
	v_mov_b32_e32 v107, 0
	v_mad_u32_u24 v175, v170, s8, v2
	v_mov_b32_e32 v2, s4
	v_readlane_b32 s4, v253, 48
	v_lshrrev_b32_e32 v1, 4, v0
	s_mov_b32 s6, 0xc000
	v_mov_b32_e32 v3, 0x6000
	v_mov_b32_e32 v115, v107
	v_readlane_b32 s5, v253, 49
	v_mul_u32_u24_e32 v173, 0xc000, v1
	v_mad_u32_u24 v174, v1, s6, v3
	v_lshl_add_u64 v[116:117], s[4:5], 0, v[114:115]
	s_movk_i32 s4, 0x140
	v_lshlrev_b32_e32 v7, 2, v1
	v_or_b32_e32 v1, s25, v105
	s_movk_i32 s6, 0x120
	v_mad_u32_u24 v6, v105, s4, 0
	v_mul_lo_u32 v9, v1, s6
	s_movk_i32 s6, 0xff60
	s_cmpk_lt_u32 s12, 0x100
	v_mad_u32_u24 v177, v170, s8, v2
	v_mad_i32_i24 v10, v105, s6, v6
	s_cselect_b64 s[6:7], -1, 0
	v_lshlrev_b32_e32 v2, 7, v105
	s_lshl_b32 s9, s9, 5
	v_readlane_b32 s14, v253, 46
	v_lshlrev_b32_e32 v172, 2, v105
	v_lshlrev_b32_e32 v106, 2, v170
	v_mov_b32_e32 v113, v107
	v_add3_u32 v11, v10, v2, s9
	v_readlane_b32 s15, v253, 47
	v_lshl_add_u32 v2, v0, 4, 0
	v_lshl_add_u64 v[120:121], s[2:3], 0, v[106:107]
	v_lshl_add_u64 v[122:123], s[14:15], 0, v[112:113]
	v_add_u32_e32 v113, 0x2800, v2
	v_lshl_or_b32 v2, v173, 1, v172
	v_lshl_or_b32 v106, s26, 6, v172
	v_or_b32_e32 v179, 0x4000, v2
	v_add_u32_e32 v180, 0x10000, v2
	v_lshl_add_u64 v[2:3], s[2:3], 0, v[106:107]
	s_mov_b64 s[2:3], 0x100
	v_lshrrev_b32_e32 v167, 4, v166
	v_lshl_add_u64 v[128:129], v[2:3], 0, s[2:3]
	s_lshr_b32 s2, s12, 3
	v_mul_u32_u24_e32 v4, 0x6000, v170
	v_lshlrev_b32_e32 v176, 3, v167
	v_readlane_b32 s4, v253, 50
	v_readlane_b32 s14, v253, 30
	v_readlane_b32 s76, v253, 32
	v_readlane_b32 s30, v253, 2
	s_and_b32 s2, s2, 0x1fffffe0
	v_lshlrev_b32_e32 v104, 2, v167
	s_movk_i32 s0, 0x240
	v_mov_b32_e32 v111, v107
	v_mov_b32_e32 v109, v107
	v_readlane_b32 s5, v253, 51
	v_add_u32_e32 v8, 0, v102
	v_readlane_b32 s15, v253, 31
	v_readlane_b32 s77, v253, 33
	s_lshl_b32 s43, s30, 5
	v_readlane_b32 s35, v253, 45
	v_or_b32_e32 v2, s2, v176
	v_lshlrev_b32_e32 v3, 1, v4
	v_add_u32_e32 v183, v6, v7
	v_cmp_gt_u32_e64 s[0:1], s0, v0
	v_lshl_add_u64 v[118:119], s[4:5], 0, v[114:115]
	v_cmp_gt_u32_e64 s[10:11], 16, v166
	v_cmp_lt_u32_e64 s[4:5], 15, v166
	v_add_u32_e32 v171, 0, v9
	v_lshl_add_u64 v[124:125], s[14:15], 0, v[108:109]
	v_lshl_add_u64 v[126:127], s[76:77], 0, v[110:111]
	v_or_b32_e32 v178, 0xfffffe00, v0
	s_lshl_b32 s9, s35, 5
	v_add3_u32 v181, v2, v3, s8
	s_lshl_b32 s27, s25, 2
	v_lshlrev_b32_e32 v182, 2, v104
	s_mov_b32 s28, 0xffff0000
	s_mov_b64 s[2:3], 0x600000
	s_mov_b64 s[12:13], 0x8000
	v_mov_b32_e32 v2, v107
	v_mov_b32_e32 v3, v107
	v_mov_b32_e32 v4, v107
	v_mov_b32_e32 v5, v107
	v_bfrev_b32_e32 v184, 24
	v_add_u32_e32 v185, 0x1400, v183
	v_add_u32_e32 v186, v8, v9
	v_add_u32_e32 v187, v10, v102
	v_add_u32_e32 v188, v11, v176
	s_mov_b32 s29, s43
	v_writelane_b32 v253, s9, 48
	s_branch .LBB0_207

; __device__ __forceinline__ unsigned xb_ld(unsigned* p)              { return __hip_atomic_load(p, __ATOMIC_RELAXED, __HIP_MEMORY_SCOPE_AGENT); }
; __device__ __forceinline__ void xcd_barrier_complete(unsigned* bar, unsigned x, unsigned& nloc, unsigned& nx) {
;     const unsigned G = gridDim.x * gridDim.y * gridDim.z;
;     unsigned sum, cnt, mine, sp = 0u;
;     for (;;) {
;         sum = 0u; cnt = 0u; mine = 0u;
; #pragma unroll
;         for (unsigned j = 0; j < 16; ++j) { const unsigned c = xb_ld(&bar[XB_XCNT(j)]); sum += c; cnt += (c > 0u) ? 1u : 0u; mine = (j == x) ? c : mine; }
; __device__ __forceinline__ void xcd_barrier(const XcdBarrier& b) {
;     asm volatile("s_waitcnt vmcnt(0)" ::: "memory");
;     __syncthreads();
;     if (threadIdx.x == 0) {
;         unsigned* bar = b.bar;
;         __builtin_amdgcn_s_waitcnt(0);
;         unsigned nloc = b.st[0], nx = b.st[1];
;         if (nloc == 0u) { xcd_barrier_complete(bar, b.x, nloc, nx); b.st[0] = nloc; b.st[1] = nx; }
.LBB0_362:
	s_setprio 0
	v_readlane_b32 s0, v253, 22
	v_readlane_b32 s1, v253, 23
	v_readlane_b32 s2, v253, 24
	v_readlane_b32 s94, v253, 53
	s_cmp_gt_i32 s1, 4
	v_readlane_b32 s2, v253, 52
	v_readlane_b32 s92, v253, 45
	v_readlane_b32 s95, v253, 54
	v_readlane_b32 s3, v253, 25
	s_cbranch_scc0 .LBB0_412
	s_waitcnt vmcnt(0)
	v_cmp_eq_u32_e32 vcc, 0, v0
	s_waitcnt vmcnt(0) lgkmcnt(0)
	s_barrier
	s_and_saveexec_b64 s[0:1], vcc
	s_cbranch_execz .LBB0_411
	v_readlane_b32 s3, v253, 27
	s_waitcnt vmcnt(0) expcnt(0) lgkmcnt(0)
	s_nop 0
	v_mov_b32_e32 v1, s3
	ds_read_b32 v3, v1
	ds_read_b32 v1, v1 offset:4
	s_waitcnt lgkmcnt(1)
	v_cmp_ne_u32_e32 vcc, 0, v3
	s_cbranch_vccnz .LBB0_379
	v_readlane_b32 s4, v253, 0
	v_readlane_b32 s5, v253, 1
	s_load_dwordx2 s[8:9], s[4:5], 0x4
	s_add_u32 s4, s58, 0x4200
	s_addc_u32 s5, s59, 0
	s_add_u32 s6, s58, 0x4400
	s_addc_u32 s7, s59, 0
	s_waitcnt lgkmcnt(0)
	s_mul_i32 s3, s8, s92
	s_add_u32 s8, s58, 0x4500
	s_mul_i32 s3, s3, s9
	s_addc_u32 s9, s59, 0
	s_add_u32 s10, s58, 0x4600
	s_addc_u32 s11, s59, 0
	s_add_u32 s12, s58, 0x4700
	s_addc_u32 s13, s59, 0
	s_add_u32 s14, s58, 0x4800
	s_addc_u32 s15, s59, 0
	s_add_u32 s16, s58, 0x4900
	s_addc_u32 s17, s59, 0
	s_add_u32 s18, s58, 0x4a00
	s_addc_u32 s19, s59, 0
	s_add_u32 s20, s58, 0x4b00
	s_addc_u32 s21, s59, 0
	s_add_u32 s22, s58, 0x4c00
	s_addc_u32 s23, s59, 0
	s_add_u32 s24, s58, 0x4d00
	s_addc_u32 s25, s59, 0
	s_add_u32 s26, s58, 0x4e00
	s_addc_u32 s27, s59, 0
	s_add_u32 s28, s58, 0x4f00
	s_addc_u32 s29, s59, 0
	s_add_u32 s30, s58, 0x5000
	s_addc_u32 s31, s59, 0
	s_add_u32 s34, s58, 0x5100
	s_addc_u32 s35, s59, 0
	s_add_u32 s36, s58, 0x5200
	s_addc_u32 s37, s59, 0
	s_add_u32 s38, s58, 0x5300
	s_addc_u32 s39, s59, 0
	s_mov_b32 s33, 1
	v_mov_b32_e32 v17, 0
	s_branch .LBB0_367

; #define LAS __attribute__((address_space(3)))
; DI void ssd_unit(Frame& F, const Mix1Args& a, int u) {
;     const int tid = F.tid, w = F.wave, lane = F.lane, fr = lane & 15, fq = lane >> 4;
;     const int b = u >> 7, h = u & 127, g = h >> 4;
;     constexpr int O_XDT = 0, O_XDS = 64 * S64, O_MM = 2 * 64 * S64, IMG = 3 * 64 * S64;
;     LAS uchar* IMG0 = F.lds; LAS uchar* SB0 = IMG0 + 2 * IMG; LAS float* TAB = (LAS float*)(SB0 + 2 * 64 * S128) + w * 128;
;     const int c2x = tid & 31, rg4 = tid >> 5;
;     float xw[4][2], xb[2];
; #pragma unroll
;     for (int j = 0; j < 2; ++j) { const int chx = h * 64 + 2 * c2x + j; xb[j] = a.conv_b[chx];
; #pragma unroll
;         for (int k = 0; k < 4; ++k) xw[k][j] = a.conv_w[k * 10240 + chx]; }
;     const float Dh = a.d_skip[h];
;     const int ltile = w & 3, l0_ = 16 * ltile, ph = (w >> 2) * 2;
;     const size_t rowbase = (size_t)b * SEQ;
;     const unsigned vo16 = (unsigned)tid * 16u, vot = (unsigned)lane * 4u;
;     const unsigned voc = (unsigned)((ltile * 256 + lane) * 16), vob = (unsigned)((w * 128 + lane) * 16);
;     unsigned vox[7];
; #pragma unroll
;     for (int i = 0; i < 7; ++i) vox[i] = (unsigned)((4 * rg4 + i) * N3P + C_X + h * 64 + 2 * c2x) * 2u;
;     const unsigned voz = (unsigned)((l0_ + fr) * N3P + C_Z + h * 64 + 16 * ph + 4 * fq) * 2u;
;     const unsigned voo = (unsigned)((l0_ + fr) * a.out_ld + a.o_col + h * 64 + 16 * ph + 4 * fq) * 2u, vos = (unsigned)(l0_ + fr) * 4u;
;     const char* const pC = (const char*)a.Cg; const char* const pB = (const char*)a.BTg; const char* const pCB = (const char*)a.CBg;
;     const char* const pP = (const char*)a.proj; const char* const pT = (const char*)a.TABg; char* const pO = (char*)a.outp; char* const pS = (char*)a.ssq_y;
;     for (int i = tid; i < 64 * S128 / 16; i += 512) ((LAS u32x4*)SB0)[i] = (u32x4){0u, 0u, 0u, 0u};
;     ...
;         { const int l = tid >> 3, m8 = (tid & 7) * 8; u32x4 p = (u32x4){0u, 0u, 0u, 0u}; const u32x4 cbc = c.cb;
;           if (m8 <= l) { const float csl = TAB[l]; const float dsk = Dh * frcp(fmaxf(TAB[64 + l], 1e-20f)); const f32x4 ca = *(const LAS f32x4*)(TAB + m8), cb4 = *(const LAS f32x4*)(TAB + m8 + 4);
;               float mv[8];
; #pragma unroll
;               for (int j = 0; j < 8; ++j) { const unsigned wv = j < 2 ? cbc.x : j < 4 ? cbc.y : j < 6 ? cbc.z : cbc.w; const float cbv = (j & 1) ? bfhi(wv) : bflo(wv);
.LBB0_671:
	v_readlane_b32 s4, v253, 22
	v_readlane_b32 s5, v253, 23
	s_cmp_lt_i32 s4, 8
	s_cselect_b64 s[0:1], -1, 0
	s_cmp_gt_i32 s5, 7
	s_cselect_b64 s[4:5], -1, 0
	s_and_b64 s[0:1], s[0:1], s[4:5]
	s_andn2_b64 vcc, exec, s[0:1]
	v_readlane_b32 s6, v253, 24
	v_readlane_b32 s7, v253, 25
	s_cbranch_vccnz .LBB0_763
	v_readlane_b32 s0, v253, 2
	s_cmpk_gt_i32 s0, 0xff
	s_cbranch_scc1 .LBB0_713
	v_readlane_b32 s6, v253, 41
	v_readlane_b32 s7, v253, 42
	s_and_b64 s[0:1], s[6:7], exec
	v_readlane_b32 s0, v253, 44
	s_cselect_b32 s39, s51, s0
	v_readlane_b32 s0, v253, 43
	s_cselect_b32 s38, s50, s0
	s_add_u32 s4, s58, 0x50000000
	s_addc_u32 s5, s59, 0
	s_and_b64 s[0:1], s[6:7], exec
	v_readlane_b32 s0, v253, 28
	s_cselect_b32 s44, s0, s4
	v_lshrrev_b32_e32 v5, 5, v0
	s_mov_b32 s4, 0x24800
	v_mov_b32_e32 v8, 0x9200
	s_waitcnt vmcnt(0)
	v_mad_u32_u24 v170, v5, s4, v8
	v_mov_b32_e32 v8, 0x12400
	v_mad_u32_u24 v171, v5, s4, v8
	v_mov_b32_e32 v8, 0x1b600
	v_mad_u32_u24 v172, v5, s4, v8
	v_mov_b32_e32 v8, 0x2da00
	v_mad_u32_u24 v174, v5, s4, v8
	v_mov_b32_e32 v8, 0x36c00
	v_lshlrev_b32_e32 v9, 3, v0
	v_mad_u32_u24 v175, v5, s4, v8
	v_lshrrev_b32_e32 v8, 1, v0
	v_and_b32_e32 v9, 56, v9
	v_and_b32_e32 v176, 24, v8
	v_lshrrev_b32_e32 v8, 3, v0
	v_or_b32_e32 v10, 1, v9
	v_cmp_eq_u32_e64 s[8:9], v10, v8
	v_or_b32_e32 v10, 2, v9
	v_readlane_b32 s1, v253, 29
	v_cmp_gt_u32_e64 s[10:11], v10, v8
	v_cmp_eq_u32_e64 s[12:13], v10, v8
	v_or_b32_e32 v10, 3, v9
	s_cselect_b32 s45, s1, s5
	s_mov_b32 s46, 0x9200
	v_readlane_b32 s66, v253, 26
	v_readlane_b32 s1, v253, 34
	v_cmp_gt_u32_e64 s[14:15], v10, v8
	v_cmp_eq_u32_e64 s[16:17], v10, v8
	v_or_b32_e32 v10, 4, v9
	s_cselect_b32 s86, s46, 0x4000
	s_cmp_gt_u32 s66, 3
	s_cbranch_scc0 .Lssd_noprio
	s_setprio 1
.Lssd_noprio:
	s_lshl_b32 s0, s66, 9
	s_bfe_u32 s36, s1, 0x20006
	s_lshr_b32 s1, s1, 7
	v_cmp_gt_u32_e64 s[18:19], v10, v8
	v_cmp_eq_u32_e64 s[20:21], v10, v8
	v_or_b32_e32 v10, 5, v9
	v_and_b32_e32 v2, 15, v0
	v_lshlrev_b32_e32 v6, 4, v166
	s_add_i32 s87, s0, 0
	s_and_b32 s62, s1, 0x1fffffe
	v_cmp_gt_u32_e64 s[22:23], v10, v8
	v_cmp_eq_u32_e64 s[24:25], v10, v8
	v_or_b32_e32 v10, 6, v9
	s_add_i32 s87, s87, 0x18000
	v_lshl_or_b32 v86, s36, 12, v6
	v_lshl_or_b32 v88, s66, 11, v6
	v_lshl_or_b32 v6, s36, 4, v2
	s_lshl_b32 s63, s62, 5
	v_cmp_gt_u32_e64 s[26:27], v10, v8
	v_cmp_eq_u32_e64 s[28:29], v10, v8
	v_or_b32_e32 v10, 7, v9
	s_movk_i32 s64, 0xa0
	v_lshl_or_b32 v13, s62, 4, v2
	s_movk_i32 s62, 0x120
	v_and_b32_e32 v3, 31, v0
	v_mad_u32_u24 v173, v5, s4, s4
	v_cmp_le_u32_e64 s[40:41], v9, v8
	v_lshl_add_u32 v181, v8, 2, s87
	v_cmp_eq_u32_e64 s[4:5], v9, v8
	v_cmp_lt_u32_e64 s[6:7], v9, v8
	v_cmp_gt_u32_e64 s[30:31], v10, v8
	v_cmp_eq_u32_e64 s[34:35], v10, v8
	v_mad_u32_u24 v8, v8, s64, 0
	v_and_b32_e32 v12, 48, v0
	v_mul_lo_u32 v185, v13, s62
	v_mad_u32_u24 v15, v6, s64, 0
	v_mul_lo_u32 v13, v13, s64
	s_add_i32 s64, 0, 0x13800
	s_lshl_b32 s66, s66, 5
	v_lshlrev_b32_e32 v7, 2, v3
	v_mul_u32_u24_e32 v167, 0x24800, v5
	s_add_i32 s67, s66, s64
	v_add_u32_e32 v18, s64, v12
	s_add_i32 s64, s66, 0
	v_or_b32_e32 v1, 0x4000, v7
	v_lshlrev_b32_e32 v84, 4, v0
	s_lshl_b32 s65, s36, 6
	v_mov_b32_e32 v19, s64
	v_or_b32_e32 v7, v167, v7
	v_lshlrev_b32_e32 v90, 2, v6
	v_mov_b32_e32 v91, 0
	s_movk_i32 s37, 0x140
	s_add_i32 s36, s87, s65
	v_lshlrev_b32_e32 v11, 2, v2
	v_mov_b32_e32 v17, s67
	v_mad_u32_u24 v186, v2, s62, v19
	v_add_u32_e32 v19, 0, v84
	v_add_u32_e32 v189, 0x4000, v7
	v_add_u32_e32 v190, 0xd200, v7
	v_add_u32_e32 v191, 0x16400, v7
	v_add_u32_e32 v192, 0x28800, v7
	v_add_u32_e32 v193, 0x31a00, v7
	v_add_u32_e32 v194, 0x3ac00, v7
	v_mov_b32_e32 v7, s63
	v_lshlrev_b32_e32 v4, 1, v3
	v_lshlrev_b32_e32 v82, 2, v166
	s_mov_b32 s47, 0
	v_mul_u32_u24_e32 v177, 0x9200, v6
	v_mul_u32_u24_e32 v179, s86, v6
	v_mov_b32_e32 v85, v91
	v_lshl_add_u32 v182, v9, 2, s87
	v_lshlrev_b32_e32 v9, 1, v9
	v_lshlrev_b32_e32 v10, 4, v5
	v_mad_u32_u24 v3, v3, s37, 0
	v_lshlrev_b32_e32 v5, 3, v5
	v_lshl_add_u64 v[94:95], s[38:39], 0, v[90:91]
	v_add_u32_e32 v184, 0, v12
	v_add_u32_e32 v14, 0x1200, v185
	v_mul_u32_u24_e32 v16, 0xa0, v2
	v_mad_u32_u24 v17, v2, s62, v17
	v_add_u32_e32 v2, 0xf000, v186
	v_add_u32_e32 v187, 0xf000, v19
	v_mad_u32_u24 v19, v6, s46, v7
	v_or_b32_e32 v90, s65, v11
	s_add_u32 s88, s44, 32
	v_mad_u32_u24 v6, s86, v6, v7
	v_readlane_b32 s92, v253, 2
	v_or_b32_e32 v178, s63, v176
	v_cmp_lt_u32_e64 s[0:1], 31, v0
	v_mov_b32_e32 v83, v91
	v_mov_b32_e32 v87, v91
	v_mov_b32_e32 v89, v91
	v_add_u32_e32 v180, s87, v82
	v_add_u32_e32 v183, s36, v11
	v_lshl_add_u64 v[92:93], s[52:53], 0, v[84:85]
	v_cmp_gt_u32_e64 s[36:37], 16, v166
	v_or_b32_e32 v188, 0xfffffe00, v0
	v_or_b32_e32 v195, v19, v176
	v_or_b32_e32 v96, 0x49b20800, v86
	v_mov_b32_e32 v97, v91
	v_lshl_add_u64 v[98:99], s[38:39], 0, v[90:91]
	s_addc_u32 s89, s45, 0
	s_lshl_b32 s90, s86, 13
	v_or_b32_e32 v196, v6, v176
	s_lshl_b32 s62, s86, 7
	s_mov_b32 s63, s47
	v_lshlrev_b32_e32 v197, 2, v4
	v_add_u32_e32 v198, v184, v14
	v_add_u32_e32 v199, v17, v176
	v_add_u32_e32 v200, v18, v185
	v_add_u32_e32 v201, v2, v176
	s_mov_b64 s[64:65], 0x490000
	s_mov_b64 s[66:67], 0x40000
	v_mov_b32_e32 v228, v91
	v_mov_b32_e32 v229, v91
	v_mov_b32_e32 v230, v91
	v_mov_b32_e32 v231, v91
	v_add_u32_e32 v202, v8, v9
	v_add_u32_e32 v203, s87, v10
	v_add_u32_e32 v204, v3, v5
	v_add_u32_e32 v205, v15, v12
	v_add_u32_e32 v206, v184, v13
	v_add_u32_e32 v207, v184, v16
	s_mov_b32 s91, s92
	s_branch .LBB0_675

; __device__ __forceinline__ unsigned xb_ld(unsigned* p)              { return __hip_atomic_load(p, __ATOMIC_RELAXED, __HIP_MEMORY_SCOPE_AGENT); }
; __device__ __forceinline__ void xcd_barrier_complete(unsigned* bar, unsigned x, unsigned& nloc, unsigned& nx) {
;     const unsigned G = gridDim.x * gridDim.y * gridDim.z;
;     unsigned sum, cnt, mine, sp = 0u;
;     for (;;) {
;         sum = 0u; cnt = 0u; mine = 0u;
; #pragma unroll
;         for (unsigned j = 0; j < 16; ++j) { const unsigned c = xb_ld(&bar[XB_XCNT(j)]); sum += c; cnt += (c > 0u) ? 1u : 0u; mine = (j == x) ? c : mine; }
; __device__ __forceinline__ void xcd_barrier(const XcdBarrier& b) {
;     asm volatile("s_waitcnt vmcnt(0)" ::: "memory");
;     __syncthreads();
;     if (threadIdx.x == 0) {
;         unsigned* bar = b.bar;
;         __builtin_amdgcn_s_waitcnt(0);
;         unsigned nloc = b.st[0], nx = b.st[1];
;         if (nloc == 0u) { xcd_barrier_complete(bar, b.x, nloc, nx); b.st[0] = nloc; b.st[1] = nx; }
.LBB0_713:
	s_setprio 0
	v_readlane_b32 s4, v253, 22
	v_readlane_b32 s5, v253, 23
	s_cmp_gt_i32 s5, 8
	v_readlane_b32 s92, v253, 45
	v_readlane_b32 s6, v253, 24
	v_readlane_b32 s7, v253, 25
	s_cbranch_scc0 .LBB0_763
	s_waitcnt vmcnt(0)
	v_cmp_eq_u32_e32 vcc, 0, v0
	s_waitcnt vmcnt(0) lgkmcnt(0)
	s_barrier
	s_and_saveexec_b64 s[0:1], vcc
	s_cbranch_execz .LBB0_762
	v_readlane_b32 s3, v253, 27
	s_waitcnt vmcnt(0) expcnt(0) lgkmcnt(0)
	s_nop 0
	v_mov_b32_e32 v1, s3
	ds_read_b32 v3, v1
	ds_read_b32 v1, v1 offset:4
	s_waitcnt lgkmcnt(1)
	v_cmp_ne_u32_e32 vcc, 0, v3
	s_cbranch_vccnz .LBB0_730
	v_readlane_b32 s4, v253, 0
	v_readlane_b32 s5, v253, 1
	s_load_dwordx2 s[8:9], s[4:5], 0x4
	s_add_u32 s4, s58, 0x4200
	s_addc_u32 s5, s59, 0
	s_add_u32 s6, s58, 0x4400
	s_addc_u32 s7, s59, 0
	s_waitcnt lgkmcnt(0)
	s_mul_i32 s3, s8, s92
	s_add_u32 s8, s58, 0x4500
	s_mul_i32 s3, s3, s9
	s_addc_u32 s9, s59, 0
	s_add_u32 s10, s58, 0x4600
	s_addc_u32 s11, s59, 0
	s_add_u32 s12, s58, 0x4700
	s_addc_u32 s13, s59, 0
	s_add_u32 s14, s58, 0x4800
	s_addc_u32 s15, s59, 0
	s_add_u32 s16, s58, 0x4900
	s_addc_u32 s17, s59, 0
	s_add_u32 s18, s58, 0x4a00
	s_addc_u32 s19, s59, 0
	s_add_u32 s20, s58, 0x4b00
	s_addc_u32 s21, s59, 0
	s_add_u32 s22, s58, 0x4c00
	s_addc_u32 s23, s59, 0
	s_add_u32 s24, s58, 0x4d00
	s_addc_u32 s25, s59, 0
	s_add_u32 s26, s58, 0x4e00
	s_addc_u32 s27, s59, 0
	s_add_u32 s28, s58, 0x4f00
	s_addc_u32 s29, s59, 0
	s_add_u32 s30, s58, 0x5000
	s_addc_u32 s31, s59, 0
	s_add_u32 s34, s58, 0x5100
	s_addc_u32 s35, s59, 0
	s_add_u32 s36, s58, 0x5200
	s_addc_u32 s37, s59, 0
	s_add_u32 s38, s58, 0x5300
	s_addc_u32 s39, s59, 0
	s_mov_b32 s33, 1
	v_mov_b32_e32 v17, 0
	s_branch .LBB0_718
